# v026 grid barrier: all blocks poll TOP count, 3 fewer dependent round trips
# speedup vs baseline: 1.0426x; 1.0088x over previous
; #define WAIT_VM(n) do {} while (0)
; #define WAIT_VM(n) asm volatile("s_waitcnt vmcnt(" #n ")" ::: "memory")
; DEV unsigned xb_ld(unsigned* p) { return __hip_atomic_load(p, __ATOMIC_RELAXED, __HIP_MEMORY_SCOPE_AGENT); }
; DEV unsigned xb_add(unsigned* p, unsigned v) { return __hip_atomic_fetch_add(p, v, __ATOMIC_RELAXED, __HIP_MEMORY_SCOPE_AGENT); }
; DEV void fence_acquire() { __builtin_amdgcn_fence(__ATOMIC_ACQUIRE, "agent"); }
; DEV void fence_release() { __builtin_amdgcn_fence(__ATOMIC_RELEASE, "agent"); }
; #define XB_SPIN(cond, bar) do { unsigned _sp = 0; while (cond) { s_sleep1(); \
;     if ((++_sp & 255u) == 0u) { if (xb_ld(&(bar)[XB_TMO])) break; if (_sp > XB_SPIN_CAP) { xb_add(&(bar)[XB_TMO], 1u); break; } } } } while (0)
; DEV void xcd_barrier(const XcdBarrier& b) {
;     ...
;         const unsigned old = xb_add(&bar[XB_XSUB(bx)], 1u);
;         const unsigned gen = old / nloc;
;         if (old + 1u == (gen + 1u) * nloc) {
;             fence_release();
;             WAIT_VM(0);
;             const unsigned og = xb_add(&bar[XB_TOP], 1u);
;             const unsigned tg = og / nx;
;             if (og + 1u == (tg + 1u) * nx) xb_add(&bar[XB_TOPGEN], 1u);
;             else XB_SPIN(xb_ld(&bar[XB_TOPGEN]) == tg, bar);
;             fence_acquire();
;             xb_add(&bar[XB_XGEN(bx)], 1u);
;             WAIT_VM(0);
;         } else {
;             XB_SPIN(xb_ld(&bar[XB_XGEN(bx)]) == gen, bar);
;             fence_acquire();
;             WAIT_VM(0);
;         }
.LBB0_86:
	s_lshl_b32 s20, s33, 6
	s_add_i32 s2, s20, 0x500
	s_mov_b32 s3, 0
	s_lshl_b64 s[0:1], s[2:3], 2
	s_add_u32 s0, s34, s0
	s_addc_u32 s1, s35, s1
	v_mov_b32_e32 v1, 1
	v_mov_b64_e32 v[4:5], s[0:1]
	flat_atomic_add v1, v[4:5], v1 sc0
	v_cvt_f32_u32_e32 v3, v2
	v_sub_u32_e32 v4, 0, v2
	v_rcp_iflag_f32_e32 v3, v3
	s_nop 0
	v_mul_f32_e32 v3, 0x4f7ffffe, v3
	v_cvt_u32_f32_e32 v3, v3
	v_mul_lo_u32 v4, v4, v3
	v_mul_hi_u32 v4, v3, v4
	v_add_u32_e32 v3, v3, v4
	s_waitcnt vmcnt(0) lgkmcnt(0)
	v_mul_hi_u32 v3, v1, v3
	v_mul_lo_u32 v5, v3, v2
	v_add_u32_e32 v4, 1, v1
	v_sub_u32_e32 v1, v1, v5
	v_add_u32_e32 v6, 1, v3
	v_cmp_ge_u32_e32 vcc, v1, v2
	v_sub_u32_e32 v5, v1, v2
	s_nop 0
	v_cndmask_b32_e32 v3, v3, v6, vcc
	v_cndmask_b32_e32 v1, v1, v5, vcc
	v_add_u32_e32 v5, 1, v3
	v_cmp_ge_u32_e32 vcc, v1, v2
	s_nop 1
	v_cndmask_b32_e32 v1, v3, v5, vcc
	v_mad_u64_u32 v[2:3], s[0:1], v2, v1, v[2:3]
	v_cmp_eq_u32_e32 vcc, v4, v2
	v_add_u32_e32 v1, 1, v1
	v_mul_lo_u32 v1, v1, v0
	s_add_u32 s0, s34, 0x3400
	s_addc_u32 s1, s35, 0
	v_mov_b64_e32 v[2:3], s[0:1]
	v_mov_b32_e32 v26, 0
	s_cbranch_vccz .Lxb0_poll
	buffer_wbl2 sc1
	s_waitcnt vmcnt(0)
	v_mov_b32_e32 v4, 1
	global_atomic_add v[2:3], v4, off
.Lxb0_poll:
	global_load_dword v4, v[2:3], off sc1
	s_waitcnt vmcnt(0)
	v_cmp_ge_u32_e32 vcc, v4, v1
	s_cbranch_vccnz .Lxb0_done
	s_sleep 1
	v_add_u32_e32 v26, 1, v26
	v_cmp_gt_u32_e32 vcc, 0x400000, v26
	s_cbranch_vccnz .Lxb0_poll
.Lxb0_done:
	buffer_inv sc1
	s_waitcnt vmcnt(0)

; #define LAS __attribute__((address_space(3)))
; DEV int readfirstlane_i(int v) { return __builtin_amdgcn_readfirstlane(v); }
;     ...
;     const int odd = l & 1; const int nlin = B_ * (odd ? 4 : 8) * 2 * 4; const int ns5 = odd ? B_ * 2 * 32 : 0;
;     const int vcu = (F.G % 8 == 0) ? (F.bid % 8) * (F.G / 8) + F.bid / 8 : F.bid;
; __global__ void __launch_bounds__(NTHREADS, 2) mega_fwd(Args args) {
;     ...
;     F.tid = threadIdx.x; F.lane = F.tid & 63; F.wave = readfirstlane_i(F.tid >> 6); F.G = gridDim.x; F.bid = blockIdx.x;
;     F.gw = F.bid * NWAVES + F.wave; F.NGW = F.G * NWAVES;
;     for (int u = F.tid; u < (LDS_BYTES - LDS_MISC) / 4; u += NTHREADS) ((LAS unsigned*)(lds + LDS_MISC))[u] = 0u;
;     __syncthreads();
;     XcdBarrier bar = xcd_barrier_post((unsigned*)(F.ws + WS_CTL), (volatile LAS unsigned*)(lds + LDS_MISC), F.wave);
;     ...
;     const int vcu = (F.G % 8 == 0) ? (F.bid % 8) * (F.G / 8) + F.bid / 8 : F.bid;
.Lbw1_skip:
	s_waitcnt lgkmcnt(0)
	v_readlane_b32 s38, v255, 61
	s_cmp_lg_u32 s38, 0
	s_ashr_i32 s81, s95, 31
	s_lshr_b32 s0, s81, 29
	s_add_i32 s0, s95, s0
	s_ashr_i32 s6, s0, 3
	s_and_b32 s0, s0, -8
	s_sub_i32 s7, s95, s0
	s_cmp_gt_i32 s7, 3
	s_cselect_b64 s[0:1], -1, 0
	v_writelane_b32 v252, s0, 6
	s_ashr_i32 s83, s96, 31
	s_movk_i32 s88, 0x1600
	v_writelane_b32 v252, s1, 7
	s_add_i32 s0, s7, -4
	v_writelane_b32 v252, s0, 8
	s_movk_i32 s84, 0x10ff
	v_readlane_b32 s0, v252, 5
	s_add_i32 s0, s0, s95
	s_cmpk_gt_i32 s95, 0xff
	v_writelane_b32 v252, s0, 9
	s_cselect_b64 s[0:1], -1, 0
	v_writelane_b32 v252, s0, 10
	v_mov_b32_e32 v1, 0
	v_mov_b32_e32 v202, 1
	v_writelane_b32 v252, s1, 11
	s_mul_hi_i32 s0, s95, 0x78787879
	s_ashr_i32 s1, s0, 6
	s_lshr_b32 s2, s0, 31
	s_ashr_i32 s0, s0, 5
	s_add_i32 s0, s0, s2
	s_and_b32 s8, s0, 1
	s_mulk_i32 s0, 0x44
	s_sub_i32 s0, s95, s0
	s_add_i32 s4, s1, s2
	s_lshl_b32 s9, s0, 6
	s_cmp_lt_i32 s0, 4
	s_cselect_b64 s[0:1], -1, 0
	s_add_i32 s2, s9, 0xffffff00
	s_sub_i32 s3, 0x10ff, s9
	s_sub_i32 s5, 0xff, s9
	v_writelane_b32 v252, s0, 12
	s_cmp_eq_u32 s8, 0
	v_mov_b32_e32 v203, 0x260
	v_writelane_b32 v252, s1, 13
	s_cselect_b64 s[0:1], -1, 0
	v_writelane_b32 v252, s0, 14
	v_mov_b32_e32 v204, 0x3ecc95a3
	v_mov_b32_e32 v205, 0x2000
	v_writelane_b32 v252, s1, 15
	s_and_b64 s[0:1], s[0:1], exec
	s_cselect_b32 s0, s2, s3
	v_writelane_b32 v252, s0, 16
	s_cselect_b32 s0, s9, s5
	v_writelane_b32 v252, s9, 17
	s_addk_i32 s0, 0x4000
	v_writelane_b32 v252, s0, 18
	s_ashr_i32 s1, s96, 3
	v_writelane_b32 v252, s8, 19
	s_lshl_b32 s0, s8, 2
	s_mul_i32 s1, s1, s7
	v_writelane_b32 v252, s0, 20
	s_and_b32 s0, s96, 7
	s_add_i32 s1, s1, s6
	s_add_i32 s2, s96, 0xffffff80
	v_writelane_b32 v252, s6, 21
	s_cmp_lt_i32 s7, 0
	v_writelane_b32 v252, s2, 22
	s_cselect_b64 s[2:3], -1, 0
	s_cmp_eq_u32 s0, 0
	v_writelane_b32 v252, s7, 23
	s_cselect_b32 s9, s1, s95
	v_writelane_b32 v252, s2, 24
	s_cmpk_gt_i32 s9, 0x7f
	s_cselect_b64 s[0:1], -1, 0
	v_writelane_b32 v252, s3, 25
	v_writelane_b32 v252, s0, 26
	s_ashr_i32 s2, s9, 2
	s_add_i32 s10, s9, 0xffffff80
	v_writelane_b32 v252, s1, 27
	s_ashr_i32 s0, s9, 3
	s_lshr_b32 s1, s0, 30
	s_add_i32 s1, s0, s1
	s_and_b32 s1, s1, 0x1fffffc
	s_sub_i32 s0, s0, s1
	s_lshr_b32 s1, s2, 29
	s_add_i32 s1, s2, s1
	s_lshl_b32 s0, s0, 7
	s_and_b32 s5, s9, 3
	s_bfe_i32 s3, s2, 0x10000
	s_and_b32 s6, s2, 1
	s_ashr_i32 s7, s1, 3
	s_ashr_i32 s1, s0, 31
	s_cmp_eq_u32 s6, 0
	s_mul_i32 s12, s2, 0x44
	s_cselect_b64 s[14:15], -1, 0
	s_lshl_b32 s2, s7, 8
	s_add_i32 s8, s2, 0x4000
	s_and_b32 s2, s3, 0xff
	v_writelane_b32 v252, s8, 28
	s_or_b32 s8, s8, s2
	s_and_b64 s[2:3], s[14:15], exec
	s_cselect_b32 s2, s88, 0xffffea00
	v_writelane_b32 v252, s2, 29
	s_mul_hi_i32 s2, s8, 0x1600
	v_writelane_b32 v252, s2, 30
	s_mul_i32 s2, s8, 0x1600
	s_cselect_b32 s11, 0, -1
	v_writelane_b32 v252, s2, 31
	s_lshl_b32 s2, s5, 6
	s_ashr_i32 s13, s12, 31
	v_writelane_b32 v252, s2, 32
	s_lshl_b64 s[2:3], s[12:13], 11
	v_writelane_b32 v252, s2, 33
	v_writelane_b32 v253, s10, 0
	v_mov_b32_e32 v206, 0x3727c5ac
	v_writelane_b32 v252, s3, 34
	s_lshl_b64 s[2:3], s[12:13], 13
	v_writelane_b32 v252, s2, 35
	v_mov_b32_e32 v207, 0x4400
	v_mov_b32_e32 v208, 0x3db504f3
	v_writelane_b32 v252, s3, 36
	s_mov_b32 s2, s12
	v_writelane_b32 v252, s2, 37
	v_mov_b32_e32 v209, 0x7f800000
	v_mov_b32_e32 v146, 0x3f317218
	v_writelane_b32 v252, s3, 38
	s_lshl_b64 s[2:3], s[12:13], 14
	v_writelane_b32 v252, s2, 39
	s_mov_b32 s13, s11
	v_mov_b32_e32 v210, 0x10ff
	v_writelane_b32 v252, s3, 40
	s_lshl_b32 s2, s7, 12
	v_writelane_b32 v252, s2, 41
	s_movk_i32 s7, 0x800
	v_writelane_b32 v252, s14, 42
	s_and_b64 s[2:3], s[14:15], exec
	s_cselect_b32 s12, s7, 0xfffff800
	s_abs_i32 s3, s54
	v_cvt_f32_u32_e32 v0, s3
	v_writelane_b32 v252, s15, 43
	v_writelane_b32 v252, s11, 44
	s_mul_i32 s2, s6, 0x4400
	v_writelane_b32 v252, s2, 45
; #define WAIT_VM(n) do {} while (0)
; #define LAS __attribute__((address_space(3)))
; #define GAS __attribute__((address_space(1)))
; #define WAIT_VM(n) asm volatile("s_waitcnt vmcnt(" #n ")" ::: "memory")
; DEV unsigned xb_ld(unsigned* p) { return __hip_atomic_load(p, __ATOMIC_RELAXED, __HIP_MEMORY_SCOPE_AGENT); }
; DEV unsigned xb_add(unsigned* p, unsigned v) { return __hip_atomic_fetch_add(p, v, __ATOMIC_RELAXED, __HIP_MEMORY_SCOPE_AGENT); }
; DEV void fence_acquire() { __builtin_amdgcn_fence(__ATOMIC_ACQUIRE, "agent"); }
; #define XB_SPIN(cond, bar) do { unsigned _sp = 0; while (cond) { s_sleep1(); \
;     if ((++_sp & 255u) == 0u) { if (xb_ld(&(bar)[XB_TMO])) break; if (_sp > XB_SPIN_CAP) { xb_add(&(bar)[XB_TMO], 1u); break; } } } } while (0)
; DEV void xcd_barrier(const XcdBarrier& b) {
;     ...
;             xb_add(&bar[XB_XGEN(bx)], 1u);
;             WAIT_VM(0);
;         } else {
;             XB_SPIN(xb_ld(&bar[XB_XGEN(bx)]) == gen, bar);
;             fence_acquire();
;             WAIT_VM(0);
;         }
;     }
;     __syncthreads();
;     const int odd = l & 1, nhh = odd ? 4 : 8;
;     ...
;     const GAS bf16_t* P = (const GAS bf16_t*)(F.ws + WS_P); const GAS bf16_t* Q = (const GAS bf16_t*)(F.ws + WS_QKV);
;     ...
;     for (int i = F.tid; i < 32 * 136 / 2; i += NTHREADS) ((LAS unsigned*)(F.lds + SQ_SB))[i] = 0u;
;     if (F.tid < 128) ((LAS float*)(F.lds + SQ_NV))[F.tid] = 0.f;
;     __syncthreads();
	s_lshl_b32 s2, s5, 5
	s_or_b32 s2, s0, s2
	v_rcp_iflag_f32_e32 v0, v0
	v_writelane_b32 v252, s2, 46
	s_ashr_i32 s2, s4, 31
	v_writelane_b32 v252, s2, 47
	s_abs_i32 s2, s4
	v_writelane_b32 v252, s2, 48
	s_abs_i32 s2, s95
	v_writelane_b32 v252, s2, 49
	v_mul_f32_e32 v0, 0x4f7ffffe, v0
	s_mul_hi_i32 s5, s12, 5
	v_cvt_u32_f32_e32 v0, v0
	v_writelane_b32 v252, s12, 50
	s_mul_i32 s4, s12, 5
	s_sub_i32 s2, 0, s3
	v_writelane_b32 v252, s13, 51
	v_writelane_b32 v252, s4, 52
	s_ashr_i32 s55, s54, 31
	v_mov_b32_e32 v211, 0xff
	v_writelane_b32 v252, s5, 53
	v_writelane_b32 v252, s3, 54
	v_readfirstlane_b32 s3, v0
	s_mul_i32 s2, s2, s3
	s_mul_hi_u32 s2, s3, s2
	s_add_i32 s2, s3, s2
	v_writelane_b32 v252, s2, 55
	s_lshl_b64 s[2:3], s[54:55], 2
	v_writelane_b32 v252, s2, 56
	s_mul_i32 s4, s96, 0x8800
	v_mov_b32_e32 v201, 0x1000
	v_writelane_b32 v252, s3, 57
	s_mul_i32 s3, s95, 0x8800
	s_mul_hi_i32 s2, s95, 0x8800
	s_add_u32 s3, s3, 0x40d54c00
	v_writelane_b32 v252, s3, 58
	s_addc_u32 s2, s2, 0
	v_writelane_b32 v252, s2, 59
	s_mul_hi_i32 s2, s96, 0x8800
	v_writelane_b32 v252, s2, 60
	s_mul_i32 s3, s9, 0x8800
	s_mul_hi_i32 s2, s9, 0x8800
	v_writelane_b32 v252, s9, 61
	s_add_u32 s5, s3, 0x40d54c00
	v_writelane_b32 v252, s5, 62
	s_addc_u32 s2, s2, 0
	s_add_i32 s3, s3, 0xffbc0000
	v_writelane_b32 v252, s2, 63
	s_mul_hi_i32 s2, s10, 0x8800
	s_add_u32 s3, s3, 0x40d54c00
	v_writelane_b32 v253, s3, 1
	s_addc_u32 s2, s2, 0
	v_writelane_b32 v253, s2, 2
	v_writelane_b32 v253, s4, 3
	s_add_i32 s2, s4, 0xffbc0000
	v_writelane_b32 v253, s2, 4
	s_lshl_b64 s[0:1], s[0:1], 1
	v_writelane_b32 v253, s0, 5
	s_add_i32 s86, 0, 0x20200
	v_mov_b32_e32 v250, 0x2200
	v_writelane_b32 v253, s1, 6
	s_add_i32 s0, 0, 0x27e00
	v_writelane_b32 v253, s0, 7
	s_add_i32 s0, 0, 0x27e04
	v_writelane_b32 v253, s0, 8
	s_add_i32 s0, 0, 0x15000
	v_writelane_b32 v253, s0, 9
	s_add_i32 s0, 0, 0x24400
	v_writelane_b32 v253, s0, 10
	s_add_i32 s0, 0, 0x23200
	v_writelane_b32 v253, s0, 11
	s_add_i32 s0, 0, 0x21000
	v_writelane_b32 v253, s0, 12
	s_add_i32 s0, 0, 0x24600
	v_writelane_b32 v253, s0, 13
	s_add_i32 s0, 0, 0xe400
	v_writelane_b32 v253, s0, 14
	s_add_i32 s0, 0, 0xe800
	v_writelane_b32 v253, s0, 15
	s_add_i32 s0, 0, 0xec00
	v_writelane_b32 v253, s0, 16
	s_add_i32 s0, 0, 0x10400
	v_writelane_b32 v253, s0, 17
	s_add_i32 s0, 0, 0xc400
	v_writelane_b32 v253, s0, 18
	s_add_i32 s0, 0, 0xc800
	v_writelane_b32 v253, s0, 19
	s_add_i32 s0, 0, 0xcc00
	v_writelane_b32 v253, s0, 20
	s_add_i32 s0, 0, 0xd000
	v_writelane_b32 v253, s0, 21
	s_add_i32 s0, 0, 0xd400
	v_writelane_b32 v253, s0, 22
	s_add_i32 s0, 0, 0xdc00
	v_writelane_b32 v253, s0, 23
	s_mov_b32 s1, 0
	v_writelane_b32 v253, s95, 24
	s_mov_b32 s52, s1
	v_writelane_b32 v253, s96, 25
	v_writelane_b32 v253, s44, 26
	s_mov_b32 s0, s82
	v_mov_b32_e32 v220, 0xba800000
	v_writelane_b32 v253, s45, 27
	v_writelane_b32 v253, s46, 28
	v_writelane_b32 v253, s47, 29
	v_writelane_b32 v253, s48, 30
	v_writelane_b32 v253, s49, 31
	v_writelane_b32 v253, s50, 32
	v_writelane_b32 v253, s51, 33
	v_writelane_b32 v253, s52, 34
	v_writelane_b32 v253, s53, 35
	v_writelane_b32 v253, s54, 36
	v_writelane_b32 v253, s55, 37
	v_writelane_b32 v253, s56, 38
	v_writelane_b32 v253, s57, 39
	v_writelane_b32 v253, s58, 40
	v_writelane_b32 v253, s59, 41
	v_writelane_b32 v253, s54, 42
	v_mov_b32_e32 v221, 0x3a800000
	v_mov_b32_e32 v222, 0x900
	v_writelane_b32 v253, s55, 43
	v_writelane_b32 v253, s0, 44
	v_mov_b32_e32 v149, 0x10000
	s_mov_b32 s94, 0xf800000
	v_writelane_b32 v253, s1, 45
	v_writelane_b32 v253, s81, 46
	v_writelane_b32 v253, s83, 47
	s_mov_b32 s97, 0x3fb8aa3b
	s_mov_b32 s80, 0xc2ce8ed0
	s_mov_b32 s85, 0x42b17218
	s_movk_i32 s89, 0x1fff
	s_mov_b64 s[90:91], 0x80
	s_mov_b32 s92, 0x3fd744fd
	v_writelane_b32 v253, s86, 48
	s_waitcnt lgkmcnt(0)
	s_barrier
	s_branch .LBB0_173
.LBB0_171:
	s_or_b64 exec, exec, s[34:35]
	s_waitcnt lgkmcnt(0)
	s_barrier

; #define WAIT_VM(n) do {} while (0)
; #define WAIT_VM(n) asm volatile("s_waitcnt vmcnt(" #n ")" ::: "memory")
; DEV unsigned xb_ld(unsigned* p) { return __hip_atomic_load(p, __ATOMIC_RELAXED, __HIP_MEMORY_SCOPE_AGENT); }
; DEV unsigned xb_add(unsigned* p, unsigned v) { return __hip_atomic_fetch_add(p, v, __ATOMIC_RELAXED, __HIP_MEMORY_SCOPE_AGENT); }
; DEV void fence_acquire() { __builtin_amdgcn_fence(__ATOMIC_ACQUIRE, "agent"); }
; DEV void fence_release() { __builtin_amdgcn_fence(__ATOMIC_RELEASE, "agent"); }
; #define XB_SPIN(cond, bar) do { unsigned _sp = 0; while (cond) { s_sleep1(); \
;     if ((++_sp & 255u) == 0u) { if (xb_ld(&(bar)[XB_TMO])) break; if (_sp > XB_SPIN_CAP) { xb_add(&(bar)[XB_TMO], 1u); break; } } } } while (0)
; DEV void xcd_barrier(const XcdBarrier& b) {
;     ...
;         const unsigned old = xb_add(&bar[XB_XSUB(bx)], 1u);
;         const unsigned gen = old / nloc;
;         if (old + 1u == (gen + 1u) * nloc) {
;             fence_release();
;             WAIT_VM(0);
;             const unsigned og = xb_add(&bar[XB_TOP], 1u);
;             const unsigned tg = og / nx;
;             if (og + 1u == (tg + 1u) * nx) xb_add(&bar[XB_TOPGEN], 1u);
;             else XB_SPIN(xb_ld(&bar[XB_TOPGEN]) == tg, bar);
;             fence_acquire();
;             xb_add(&bar[XB_XGEN(bx)], 1u);
;             WAIT_VM(0);
;         } else {
;             XB_SPIN(xb_ld(&bar[XB_XGEN(bx)]) == gen, bar);
;             fence_acquire();
;             WAIT_VM(0);
;         }
.LBB0_212:
	s_lshl_b32 s22, s0, 6
	s_add_i32 s0, s22, 0x500
	s_lshl_b64 s[2:3], s[0:1], 2
	s_add_u32 s2, s36, s2
	s_addc_u32 s3, s37, s3
	v_mov_b64_e32 v[4:5], s[2:3]
	flat_atomic_add v4, v[4:5], v202 sc0
	v_cvt_f32_u32_e32 v3, v2
	v_sub_u32_e32 v5, 0, v2
	v_rcp_iflag_f32_e32 v3, v3
	s_nop 0
	v_mul_f32_e32 v3, 0x4f7ffffe, v3
	v_cvt_u32_f32_e32 v3, v3
	v_mul_lo_u32 v5, v5, v3
	v_mul_hi_u32 v5, v3, v5
	v_add_u32_e32 v3, v3, v5
	s_waitcnt vmcnt(0) lgkmcnt(0)
	v_mul_hi_u32 v3, v4, v3
	v_mul_lo_u32 v5, v3, v2
	v_sub_u32_e32 v5, v4, v5
	v_cmp_ge_u32_e32 vcc, v5, v2
	v_add_u32_e32 v6, 1, v3
	s_nop 0
	v_cndmask_b32_e32 v3, v3, v6, vcc
	v_sub_u32_e32 v6, v5, v2
	v_cndmask_b32_e32 v5, v5, v6, vcc
	v_cmp_ge_u32_e32 vcc, v5, v2
	v_add_u32_e32 v5, 1, v3
	v_add_u32_e32 v6, 1, v4
	v_cndmask_b32_e32 v3, v3, v5, vcc
	v_mad_u64_u32 v[4:5], s[2:3], v2, v3, v[2:3]
	v_cmp_eq_u32_e32 vcc, v6, v4
	v_add_u32_e32 v3, 1, v3
	v_mul_lo_u32 v3, v3, v0
	s_add_u32 s2, s36, 0x3400
	s_addc_u32 s3, s37, 0
	v_mov_b64_e32 v[4:5], s[2:3]
	v_mov_b32_e32 v17, 0
	s_cbranch_vccz .Lxb2_poll
	buffer_wbl2 sc1
	s_waitcnt vmcnt(0)
	v_mov_b32_e32 v6, 1
	global_atomic_add v[4:5], v6, off
.Lxb2_poll:
	global_load_dword v6, v[4:5], off sc1
	s_waitcnt vmcnt(0)
	v_cmp_ge_u32_e32 vcc, v6, v3
	s_cbranch_vccnz .Lxb2_done
	s_sleep 1
	v_add_u32_e32 v17, 1, v17
	v_cmp_gt_u32_e32 vcc, 0x400000, v17
	s_cbranch_vccnz .Lxb2_poll

; #define WAIT_VM(n) do {} while (0)
; #define WAIT_VM(n) asm volatile("s_waitcnt vmcnt(" #n ")" ::: "memory")
; DEV unsigned xb_ld(unsigned* p) { return __hip_atomic_load(p, __ATOMIC_RELAXED, __HIP_MEMORY_SCOPE_AGENT); }
; DEV unsigned xb_add(unsigned* p, unsigned v) { return __hip_atomic_fetch_add(p, v, __ATOMIC_RELAXED, __HIP_MEMORY_SCOPE_AGENT); }
; DEV void fence_acquire() { __builtin_amdgcn_fence(__ATOMIC_ACQUIRE, "agent"); }
; #define XB_SPIN(cond, bar) do { unsigned _sp = 0; while (cond) { s_sleep1(); \
;     if ((++_sp & 255u) == 0u) { if (xb_ld(&(bar)[XB_TMO])) break; if (_sp > XB_SPIN_CAP) { xb_add(&(bar)[XB_TMO], 1u); break; } } } } while (0)
; DEV void xcd_barrier(const XcdBarrier& b) {
;     ...
;             else XB_SPIN(xb_ld(&bar[XB_TOPGEN]) == tg, bar);
;             fence_acquire();
;             xb_add(&bar[XB_XGEN(bx)], 1u);
;             WAIT_VM(0);
;         } else {
;             XB_SPIN(xb_ld(&bar[XB_XGEN(bx)]) == gen, bar);
;             fence_acquire();
;             WAIT_VM(0);
.Lxb4_done:
	buffer_inv sc1
	s_waitcnt vmcnt(0)
	s_branch .Lxb4_join

; #define WAIT_VM(n) do {} while (0)
; #define WAIT_VM(n) asm volatile("s_waitcnt vmcnt(" #n ")" ::: "memory")
; DEV unsigned xb_ld(unsigned* p) { return __hip_atomic_load(p, __ATOMIC_RELAXED, __HIP_MEMORY_SCOPE_AGENT); }
; DEV unsigned xb_add(unsigned* p, unsigned v) { return __hip_atomic_fetch_add(p, v, __ATOMIC_RELAXED, __HIP_MEMORY_SCOPE_AGENT); }
; DEV void fence_acquire() { __builtin_amdgcn_fence(__ATOMIC_ACQUIRE, "agent"); }
; #define XB_SPIN(cond, bar) do { unsigned _sp = 0; while (cond) { s_sleep1(); \
;     if ((++_sp & 255u) == 0u) { if (xb_ld(&(bar)[XB_TMO])) break; if (_sp > XB_SPIN_CAP) { xb_add(&(bar)[XB_TMO], 1u); break; } } } } while (0)
; DEV void xcd_barrier(const XcdBarrier& b) {
;     ...
;             fence_acquire();
;             xb_add(&bar[XB_XGEN(bx)], 1u);
;             WAIT_VM(0);
;         } else {
;             XB_SPIN(xb_ld(&bar[XB_XGEN(bx)]) == gen, bar);
;             fence_acquire();
;             WAIT_VM(0);
;         }
;     }
;     __syncthreads();
.Lxb4_join:
.LBB0_811:
	s_or_b64 exec, exec, s[34:35]
	s_cselect_b32 s38, 1, 0
	v_writelane_b32 v255, s38, 61
	v_readlane_b32 s38, v255, 59
	s_add_i32 s39, s38, 1
	v_writelane_b32 v255, s39, 59
	s_mov_b32 s41, 0
	v_readlane_b32 s39, v251, 29
	s_cmp_eq_u32 s39, 0
	s_cbranch_scc1 .Lbw4_none
	v_readlane_b32 s40, v255, 51
	s_cmp_lg_u32 s40, 0x100
	s_cbranch_scc1 .Lbw4_none
	v_readlane_b32 s40, v255, 48
	s_mul_i32 s40, s40, 7
	s_mul_i32 s38, s38, 0x700
	s_add_i32 s40, s40, s38
	s_add_i32 s40, s40, s39
	s_add_i32 s40, s40, -1
	s_cmp_lt_u32 s40, 0x11f00
	s_cbranch_scc0 .Lbw4_none
	s_mov_b32 s41, 1
	s_cmp_lt_u32 s40, 0x8000
	s_cbranch_scc1 .Lbw4_have
	s_mov_b32 s41, 2
	s_sub_i32 s40, s40, 0x8000
	s_cmp_lt_u32 s40, 0x5200
	s_cbranch_scc1 .Lbw4_have
	s_mov_b32 s41, 3
	s_sub_i32 s40, s40, 0x5200

; #define WAIT_VM(n) do {} while (0)
; #define WAIT_VM(n) asm volatile("s_waitcnt vmcnt(" #n ")" ::: "memory")
; DEV unsigned xb_ld(unsigned* p) { return __hip_atomic_load(p, __ATOMIC_RELAXED, __HIP_MEMORY_SCOPE_AGENT); }
; DEV unsigned xb_add(unsigned* p, unsigned v) { return __hip_atomic_fetch_add(p, v, __ATOMIC_RELAXED, __HIP_MEMORY_SCOPE_AGENT); }
; DEV void fence_acquire() { __builtin_amdgcn_fence(__ATOMIC_ACQUIRE, "agent"); }
; #define XB_SPIN(cond, bar) do { unsigned _sp = 0; while (cond) { s_sleep1(); \
;     if ((++_sp & 255u) == 0u) { if (xb_ld(&(bar)[XB_TMO])) break; if (_sp > XB_SPIN_CAP) { xb_add(&(bar)[XB_TMO], 1u); break; } } } } while (0)
; #define GRID_BAR() xcd_barrier(bar)
; DEV void xcd_barrier(const XcdBarrier& b) {
;     ...
;             else XB_SPIN(xb_ld(&bar[XB_TOPGEN]) == tg, bar);
;             fence_acquire();
;             xb_add(&bar[XB_XGEN(bx)], 1u);
;             WAIT_VM(0);
;         } else {
;             XB_SPIN(xb_ld(&bar[XB_XGEN(bx)]) == gen, bar);
;             fence_acquire();
;             WAIT_VM(0);
; __global__ void __launch_bounds__(NTHREADS, 2) mega_fwd(Args args) {
;     ...
;         if (l + 1 < DEPTH || TIMING_PROBE >= 0) GRID_BAR();
.Lxb13_done:
	buffer_inv sc1
	s_waitcnt vmcnt(0)
	s_getpc_b64 s[98:99]
